# drop per-tile vmcnt0 drain, hand-written G5 residual epilogue (all loads in flight), 4-group within-XCD start stagger on GEMM steps
# speedup vs baseline: 1.0061x; 1.0061x over previous
; #define opqp(x) ((x) + opqz())
; __device__ void gemm_step(const P& p, int step, int l) {
;   OPQ_IDS
;   char* ws = opqp(p.ws);
;   const int nM = NTOK / 256;
;   const bool need_ctx = l < 3;
;   int ntiles;
;   const int nbr = 1;
;   if (step == 1) ntiles = nM * (NP / BNT);
;   else if (step == 3) ntiles = nM * (2304 / BNT);
;   else if (step == 6) ntiles = 4 * nM * (2048 / BNT);
;   else if (step == 7) ntiles = nM * 32;
;   else ntiles = nM * (2048 / BNT);
;   for (int t0 = BIDX; t0 < (ntiles + 255) / 256 * 256; t0 += gridDim.x) {
;     const int t = xcd_remap(t0, BIDX, gridDim.x);
;     if (t >= ntiles) continue;
.LBB0_160:
	s_add_i32 s4, s86, 0xff
	s_and_b32 s87, s4, 0x1f00
	s_cmp_ge_i32 s74, s87
	s_cbranch_scc1 .LBB0_319
	v_writelane_b32 v249, s50, 62
	s_nop 1
	v_writelane_b32 v249, s51, 63
	s_nop 0
	v_readlane_b32 s4, v249, 42
	v_readlane_b32 s8, v249, 46
	v_readlane_b32 s9, v249, 47
	s_add_u32 s48, s8, s2
	s_addc_u32 s49, s9, s3
	s_cmp_gt_u32 s77, 53
	s_cselect_b64 s[2:3], -1, 0
	s_lshl_b32 s4, s74, 5
	s_and_b32 s96, s4, 0xe0
	s_ashr_i32 s4, s74, 3
	s_add_i32 s96, s96, s4
	v_readlane_b32 s5, v249, 43
	s_add_u32 s52, s48, 0x5e8a000
	s_addc_u32 s53, s49, 0
	v_readlane_b32 s5, v249, 55
	s_bitcmp0_b32 s5, 0
	s_mov_b32 s4, 0x1c50000
	v_readlane_b32 s6, v249, 44
	s_cselect_b32 s4, s4, 0x37862600
	v_readlane_b32 s7, v249, 45
	s_add_u32 s6, s48, s4
	s_addc_u32 s7, s49, 0
	v_writelane_b32 v248, s6, 0
	s_add_u32 s4, s48, 0x2223c000
	s_addc_u32 s75, s49, 0
	v_writelane_b32 v248, s7, 1
	v_writelane_b32 v248, s4, 2
	s_add_u32 s4, s48, 0x3c50000
	v_writelane_b32 v248, s4, 3
	s_addc_u32 s4, s49, 0
	s_add_u32 s6, s48, 0xa28b800
	v_writelane_b32 v248, s4, 5
	s_addc_u32 s7, s49, 0
	v_writelane_b32 v248, s6, 7
	v_readlane_b32 s10, v249, 48
	v_readlane_b32 s11, v249, 49
	v_writelane_b32 v248, s7, 8
	s_add_u32 s6, s48, 0x4c50000
	s_addc_u32 s7, s49, 0
	v_writelane_b32 v248, s6, 9
	s_nop 1
	v_writelane_b32 v248, s7, 10
	s_add_u32 s6, s48, 0x2663c000
	s_addc_u32 s7, s49, 0
	v_writelane_b32 v248, s6, 11
	s_nop 1
	v_writelane_b32 v248, s7, 12
	s_add_u32 s6, s48, 0x4450000
	s_addc_u32 s7, s49, 0
	v_writelane_b32 v248, s6, 13
	s_and_b64 s[24:25], s[2:3], s[28:29]
	s_lshl_b32 s2, s5, 9
	v_writelane_b32 v248, s7, 14
	s_cmp_lt_u32 s77, 18
	v_writelane_b32 v248, s2, 15
	s_cselect_b64 s[42:43], -1, 0
	s_and_b32 s2, 0xffff, s5
	s_mul_i32 s3, s2, 5
	v_writelane_b32 v248, s3, 16
	s_mul_i32 s2, s2, 0x1e000
	v_writelane_b32 v248, s2, 17
	s_and_b64 s[2:3], s[38:39], exec
	s_mov_b32 s2, 0x1dd0a000
	s_cselect_b32 s2, s2, 0x1cc0a000
	s_add_u32 s2, s8, s2
	s_addc_u32 s3, s9, 0
	v_writelane_b32 v248, s2, 18
	s_nop 1
	v_writelane_b32 v248, s3, 19
	s_lshr_b32 s2, s26, 3
	s_and_b32 s2, s2, 3
	s_cmp_eq_u32 s2, 0
	s_cbranch_scc1 .Lstag_done
.Lstag_loop:
	s_sleep 60
	s_add_i32 s2, s2, -1
	s_cmp_lg_u32 s2, 0
	s_cbranch_scc1 .Lstag_loop
.Lstag_done:
	s_branch .LBB0_164

; DEVI void gemm256(const P& p, const u16* A, int lda, const u16* Bt, int ldb, int K, int brow, int bcol, int mode,
;                         int aux, int layer, int bmode) {
;     ...
;   {
;     int r0, c0, r1, c1;
;     stage_rc(TIDX * 16, r0, c0);
;     stage_rc(TIDX * 16 + 8192, r1, c1);
;     offA0 = (r0 * lda + c0) * 2; offA1 = (r1 * lda + c1) * 2;
;     offB0 = (r0 * ldb + c0) * 2; offB1 = bmode ? offB0 + 2048 * ldb * 2 : (r1 * ldb + c1) * 2;
;   }
; __device__ void gemm_step(const P& p, int step, int l) {
;     ...
;       if (step >= 6 && !need_ctx && (pm % 17) == 0) continue;
;       gemm256(p, A, lda, Bt, ldb, K, pm * 256, pn * ncol, mode, aux, l, bmode);
.LBB0_184:
	s_mul_hi_i32 s2, s4, 0x78787879
	s_lshr_b32 s3, s2, 31
	s_ashr_i32 s2, s2, 3
	s_add_i32 s72, s2, s3
	s_mul_i32 s2, s72, 17
	s_sub_i32 s2, s4, s2
	s_cmp_eq_u32 s2, 0
	s_cselect_b64 s[2:3], -1, 0
	s_and_b64 s[2:3], s[24:25], s[2:3]
	s_and_b64 vcc, exec, s[2:3]
	s_cbranch_vccnz .LBB0_163
	v_mov_b32_e32 v130, v171
	s_mov_b32 s2, s26
	v_bfe_i32 v2, v130, 27, 1
	v_lshlrev_b32_e32 v0, 4, v130
	v_lshrrev_b32_e32 v2, 22, v2
	v_add_u32_e32 v2, v0, v2
	v_ashrrev_i32_e32 v3, 10, v2
	v_mul_i32_i24_e32 v2, 0x400, v3
	v_sub_u32_e32 v2, v0, v2
	v_lshrrev_b32_e32 v4, 4, v2
	v_bitop3_b32 v4, v4, v2, 32 bitop3:0x6c
	v_ashrrev_i32_e32 v5, 31, v4
	v_lshrrev_b32_e32 v5, 26, v5
	v_add_u32_e32 v5, v4, v5
	v_lshlrev_b32_e32 v2, 3, v3
	s_waitcnt vmcnt(14)
	v_ashrrev_i32_e32 v6, 6, v5
	v_and_b32_e32 v5, 0xc0, v5
	v_and_b32_e32 v2, -16, v2
	v_lshlrev_b32_e32 v3, 5, v3
	v_sub_u32_e32 v4, v4, v5
	v_add_u32_e32 v2, v6, v2
	v_and_b32_e32 v3, 32, v3
	v_ashrrev_i16_sdwa v4, v195, sext(v4) dst_sel:DWORD dst_unused:UNUSED_PAD src0_sel:DWORD src1_sel:BYTE_0
	v_add_u32_sdwa v3, v3, sext(v4) dst_sel:DWORD dst_unused:UNUSED_PAD src0_sel:DWORD src1_sel:WORD_0
	v_mul_lo_u32 v4, v2, s5
	s_xor_b64 s[2:3], s[46:47], -1
	v_add_lshl_u32 v136, v3, v4, 1
	s_andn2_b64 vcc, exec, s[2:3]
	s_mov_b64 s[2:3], -1
	s_cbranch_vccnz .LBB0_187
	v_lshl_add_u32 v137, s5, 12, v136
	s_mov_b64 s[2:3], 0

; #define LDS_BAR() do { asm volatile("s_waitcnt lgkmcnt(0)" ::: "memory"); __builtin_amdgcn_s_barrier(); asm volatile("" ::: "memory"); } while (0)
; DEVI void gemm256(const P& p, const u16* A, int lda, const u16* Bt, int ldb, int K, int brow, int bcol, int mode,
;                         int aux, int layer, int bmode) {
;     ...
; #pragma unroll
;   for (int ai = 0; ai < 2; ++ai)
; #pragma unroll
;     for (int bj = 0; bj < (G8 ? 2 : 1); ++bj)
; #pragma unroll
;       for (int m = 0; m < 4; ++m)
; #pragma unroll
;         for (int n = 0; n < 2; ++n) {
;           const int R = ai * HALF + wr * 64 + m * 16 + fr;
;           const int chunk = bj * 16 + wc * 4 + n * 2 + (fq >> 1);
;           f32x4 v = acc[ai][bj][m][n];
;           uint2 pk = make_uint2(pk2(v[0], v[1]), pk2(v[2], v[3]));
;           *(uint2*)(stg + R * 256 + SWZ(R, chunk) * 8 + (fq & 1) * 4) = pk;
;         }
;   LDS_BAR();
.LBB0_195:
	s_or_b64 exec, exec, s[2:3]
	v_lshrrev_b32_e32 v134, 1, v134
	v_lshlrev_b32_e32 v133, 3, v133
	v_lshlrev_b32_e32 v136, 4, v134
	v_and_b32_e32 v133, 8, v133
	v_or_b32_e32 v134, v134, v135
	v_add_u32_e32 v133, 16, v133
	v_lshlrev_b32_e32 v132, 15, v132
	v_lshlrev_b32_e32 v135, 9, v131
	v_cvt_pk_bf16_f32 v126, v126, v127
	v_cvt_pk_bf16_f32 v127, v128, v129
	v_bitop3_b32 v128, v136, v134, v131 bitop3:0x36
	v_add3_u32 v132, v133, v132, v135
	v_lshlrev_b32_e32 v128, 4, v128
	v_cvt_pk_bf16_f32 v90, v90, v91
	v_cvt_pk_bf16_f32 v91, v92, v93
	v_or_b32_e32 v92, 16, v134
	s_mov_b64 s[28:29], 0
	v_add_u32_e32 v129, v132, v128
	v_cvt_pk_bf16_f32 v110, v110, v111
	v_cvt_pk_bf16_f32 v111, v112, v113
	v_cvt_pk_bf16_f32 v98, v98, v99
	v_cvt_pk_bf16_f32 v99, v100, v101
	v_bitop3_b32 v92, v136, v92, v131 bitop3:0x36
	v_or_b32_e32 v100, 18, v134
	s_waitcnt vmcnt(0)
	ds_write2st64_b64 v129, v[110:111], v[98:99] offset0:32 offset1:48
	v_lshlrev_b32_e32 v98, 4, v92
	v_cvt_pk_bf16_f32 v92, v94, v95
	v_bitop3_b32 v94, v136, v100, v131 bitop3:0x36
	v_or_b32_e32 v133, 2, v134
	v_lshlrev_b32_e32 v94, 4, v94
	v_cvt_pk_bf16_f32 v122, v122, v123
	v_cvt_pk_bf16_f32 v123, v124, v125
	v_bitop3_b32 v124, v136, v133, v131 bitop3:0x36
	v_add_u32_e32 v95, v132, v94
	v_cvt_pk_bf16_f32 v66, v66, v67
	v_cvt_pk_bf16_f32 v67, v68, v69
	v_cvt_pk_bf16_f32 v54, v54, v55
	v_cvt_pk_bf16_f32 v55, v56, v57
	v_add_u32_e32 v56, 0x10000, v132
	v_lshlrev_b32_e32 v124, 4, v124
	ds_write2st64_b64 v95, v[66:67], v[54:55] offset0:32 offset1:48
	v_cvt_pk_bf16_f32 v54, v78, v79
	v_cvt_pk_bf16_f32 v55, v80, v81
	v_add_u32_e32 v57, v56, v128
	ds_write_b64 v57, v[54:55]
	v_cvt_pk_bf16_f32 v54, v70, v71
	v_cvt_pk_bf16_f32 v55, v72, v73
	v_add_u32_e32 v57, v56, v124
	ds_write_b64 v57, v[54:55]
	v_add_u32_e32 v57, 0x12000, v132
	v_cvt_pk_bf16_f32 v50, v50, v51
	v_cvt_pk_bf16_f32 v51, v52, v53
	v_add_u32_e32 v52, v57, v124
	ds_write_b64 v52, v[50:51]
	v_add_u32_e32 v50, 0x14000, v132
	v_cvt_pk_bf16_f32 v42, v42, v43
	v_cvt_pk_bf16_f32 v43, v44, v45
	v_add_u32_e32 v44, v50, v124
	v_add_u32_e32 v125, v132, v124
	v_cvt_pk_bf16_f32 v102, v102, v103
	v_cvt_pk_bf16_f32 v103, v104, v105
	ds_write_b64 v44, v[42:43]
	v_add_u32_e32 v42, 0x16000, v132
	v_cvt_pk_bf16_f32 v118, v118, v119
	v_cvt_pk_bf16_f32 v119, v120, v121
	v_cvt_pk_bf16_f32 v114, v114, v115
	v_cvt_pk_bf16_f32 v115, v116, v117
	ds_write2st64_b64 v125, v[102:103], v[90:91] offset0:32 offset1:48
	v_cvt_pk_bf16_f32 v90, v106, v107
	v_cvt_pk_bf16_f32 v91, v108, v109
	v_add_u32_e32 v99, v132, v98
	v_cvt_pk_bf16_f32 v93, v96, v97
	v_cvt_pk_bf16_f32 v86, v86, v87
	v_cvt_pk_bf16_f32 v87, v88, v89
	v_cvt_pk_bf16_f32 v82, v82, v83
	v_cvt_pk_bf16_f32 v83, v84, v85
	v_cvt_pk_bf16_f32 v74, v74, v75
	v_cvt_pk_bf16_f32 v75, v76, v77
	v_cvt_pk_bf16_f32 v62, v62, v63
	v_cvt_pk_bf16_f32 v63, v64, v65
	v_cvt_pk_bf16_f32 v54, v58, v59
	v_cvt_pk_bf16_f32 v55, v60, v61
	v_add_u32_e32 v58, v57, v128
	v_cvt_pk_bf16_f32 v46, v46, v47
	v_cvt_pk_bf16_f32 v47, v48, v49
	v_add_u32_e32 v48, v50, v128
	v_cvt_pk_bf16_f32 v38, v38, v39
	v_cvt_pk_bf16_f32 v39, v40, v41
	v_add_u32_e32 v40, v42, v128
	v_cvt_pk_bf16_f32 v34, v34, v35
	v_cvt_pk_bf16_f32 v35, v36, v37
	v_add_u32_e32 v36, v42, v124
	v_cvt_pk_bf16_f32 v30, v30, v31
	v_cvt_pk_bf16_f32 v31, v32, v33
	v_add_u32_e32 v32, v56, v98
	v_cvt_pk_bf16_f32 v26, v26, v27
	v_cvt_pk_bf16_f32 v27, v28, v29
	v_add_u32_e32 v28, v56, v94
	v_cvt_pk_bf16_f32 v22, v22, v23
	v_cvt_pk_bf16_f32 v23, v24, v25
	v_add_u32_e32 v24, v57, v98
	v_cvt_pk_bf16_f32 v18, v18, v19
	v_cvt_pk_bf16_f32 v19, v20, v21
	v_add_u32_e32 v20, v57, v94
	v_cvt_pk_bf16_f32 v14, v14, v15
	v_cvt_pk_bf16_f32 v15, v16, v17
	v_add_u32_e32 v16, v50, v98
	v_cvt_pk_bf16_f32 v10, v10, v11
	v_cvt_pk_bf16_f32 v11, v12, v13
	v_add_u32_e32 v12, v50, v94
	v_cvt_pk_bf16_f32 v6, v6, v7
	v_cvt_pk_bf16_f32 v7, v8, v9
	v_add_u32_e32 v8, v42, v98
	v_cvt_pk_bf16_f32 v2, v2, v3
	v_cvt_pk_bf16_f32 v3, v4, v5
	v_add_u32_e32 v4, v42, v94
	ds_write2st64_b64 v129, v[126:127], v[118:119] offset1:16
	ds_write2st64_b64 v125, v[122:123], v[114:115] offset1:16
	ds_write2st64_b64 v99, v[90:91], v[86:87] offset1:16
	ds_write2st64_b64 v95, v[92:93], v[82:83] offset1:16
	ds_write2st64_b64 v99, v[74:75], v[62:63] offset0:32 offset1:48
	ds_write_b64 v58, v[54:55]
	ds_write_b64 v48, v[46:47]
	ds_write_b64 v40, v[38:39]
	ds_write_b64 v36, v[34:35]
	ds_write_b64 v32, v[30:31]
	ds_write_b64 v28, v[26:27]
	ds_write_b64 v24, v[22:23]
	ds_write_b64 v20, v[18:19]
	ds_write_b64 v16, v[14:15]
	ds_write_b64 v12, v[10:11]
	ds_write_b64 v8, v[6:7]
	ds_write_b64 v4, v[2:3]
	s_waitcnt lgkmcnt(0)
	s_barrier
	s_mov_b64 s[2:3], -1
	s_and_b64 vcc, exec, s[36:37]
	v_and_b32_e32 v64, 16, v0
	v_readlane_b32 s26, v251, 10
	s_cbranch_vccz .LBB0_313
; DEVI void gemm256(const P& p, const u16* A, int lda, const u16* Bt, int ldb, int K, int brow, int bcol, int mode,
;                         int aux, int layer, int bmode) {
;     ...
;         } else {
;           float* xb;
;           const float* gv;
;           const float* xs;
;           if (trow == 0) {
;             xb = (float*)(ws + O_XC) + ((size_t)bb * CTXL + R) * D + col;
;             xs = (layer == 0) ? p.ctx + ((size_t)bb * CTXL + R) * D + col : xb;
;             gv = (const float*)(ws + O_MOD) + ((size_t)layer * 5 + 4) * 6144 + 4096 + col;
;           } else {
;             xb = p.out + ((size_t)bb * SEQ + (trow - CTXL) + R) * D + col;
;             xs = (layer == 0) ? p.x + ((size_t)bb * SEQ + (trow - CTXL) + R) * D + col : xb;
;             gv = (const float*)(ws + O_MOD) + ((size_t)layer * 5 + bb) * 6144 + 4096 + col;
;           }
	v_readlane_b32 s60, v249, 42
	v_readlane_b32 s64, v249, 46
	v_readlane_b32 s2, v249, 53
	s_mul_i32 s47, s72, 0xffffef00
	v_readlane_b32 s65, v249, 47
	s_add_u32 s80, s64, s28
	s_addc_u32 s81, s65, s29
	s_add_i32 s46, s47, s70
	s_and_b32 s2, s97, 0xfffffe00
	v_readlane_b32 s3, v249, 54
	s_cmpk_eq_i32 s2, 0x400
	s_cselect_b64 s[2:3], -1, 0
	s_add_i32 s5, s97, 0xfffffc80
	s_cmpk_lt_u32 s5, 0x200
	s_cselect_b64 s[6:7], -1, 0
	v_cndmask_b32_e64 v0, 0, 1, s[6:7]
	v_cndmask_b32_e64 v2, 0, 1, s[68:69]
	v_and_b32_e32 v3, 31, v130
	s_and_b64 s[2:3], s[38:39], s[2:3]
	v_cndmask_b32_e64 v0, v2, v0, s[38:39]
	v_cndmask_b32_e64 v65, 0, 1, s[2:3]
	v_cmp_gt_u32_e32 vcc, 16, v3
	v_and_b32_e32 v2, 1, v0
	v_ashrrev_i32_e32 v10, 5, v130
	v_cndmask_b32_e32 v0, v0, v65, vcc
	v_and_b32_e32 v0, 1, v0
	v_cmp_eq_u32_e32 vcc, 1, v0
	v_and_b32_e32 v0, 15, v10
	v_cmp_eq_u32_e64 s[44:45], 1, v2
	v_lshl_add_u32 v2, v3, 3, s97
	v_bitop3_b32 v0, v0, v3, v64 bitop3:0x36
	v_lshlrev_b32_e32 v8, 4, v0
	v_readlane_b32 s2, v248, 15
	v_ashrrev_i32_e32 v0, 8, v2
	s_xor_b64 s[82:83], vcc, -1
	v_add_u32_e32 v4, s2, v2
	v_lshl_add_u32 v0, s72, 2, v0
	s_movk_i32 s2, 0x1100
	s_mov_b64 s[88:89], s[84:85]
	v_mad_i64_i32 v[12:13], s[2:3], v0, s2, 0
	v_and_b32_e32 v0, 0xf8, v2
	s_add_u32 s84, s80, 0x2221a000
	v_ashrrev_i32_e32 v3, 31, v2
	v_lshlrev_b32_e32 v0, 1, v0
	s_addc_u32 s85, s81, 0
	v_lshl_add_u64 v[6:7], s[80:81], 0, v[0:1]
	s_mov_b64 s[2:3], 0x1b28a000
	v_lshlrev_b64 v[16:17], 1, v[2:3]
	s_cmp_lg_u32 s46, 0
	v_lshl_add_u64 v[14:15], v[6:7], 0, s[2:3]
	v_lshl_add_u64 v[6:7], s[80:81], 0, v[16:17]
	s_mov_b64 s[2:3], 0x1990a000
	s_cselect_b64 s[54:55], -1, 0
	s_ashr_i32 s73, s72, 31
	s_add_i32 s5, s46, 0xffffff00
	v_lshl_add_u64 v[18:19], v[6:7], 0, s[2:3]
	s_lshl_b64 s[2:3], s[72:73], 12
	s_ashr_i32 s6, s5, 31
	s_add_u32 s56, s2, s5
	v_readlane_b32 s2, v248, 16
	s_addc_u32 s57, s3, s6
	s_add_i32 s2, s2, s72
	s_mul_hi_i32 s3, s2, 0x6000
	s_mulk_i32 s2, 0x6000
	s_add_u32 s2, s80, s2
	s_addc_u32 s3, s81, s3
	s_add_u32 s58, s2, 0x5614000
	s_addc_u32 s59, s3, 0
	s_lshl_b64 s[2:3], s[72:73], 19
	v_writelane_b32 v248, s2, 20
	v_lshlrev_b64 v[20:21], 2, v[2:3]
	v_lshl_add_u64 v[2:3], s[80:81], 0, v[20:21]
	v_writelane_b32 v248, s3, 21
	s_mov_b64 s[2:3], 0x568a000
	v_lshl_add_u64 v[22:23], v[2:3], 0, s[2:3]
	v_readlane_b32 s2, v248, 17
	s_add_u32 s2, s80, s2
	s_addc_u32 s3, s81, 0
	v_readlane_b32 s61, v249, 43
	s_add_u32 s60, s2, 0x562c000
	s_addc_u32 s61, s3, 0
	s_add_u32 s2, s80, 0xa28a000
	v_readlane_b32 s8, v251, 11
	s_addc_u32 s3, s81, 0
	s_lshl_b64 s[6:7], s[34:35], 1
	v_ashrrev_i32_e32 v5, 31, v4
	v_readlane_b32 s9, v251, 12
	v_readlane_b32 s10, v251, 13
	v_readlane_b32 s11, v251, 14
	v_readlane_b32 s12, v251, 15
	v_readlane_b32 s13, v251, 16
	v_readlane_b32 s14, v251, 17
	v_readlane_b32 s15, v251, 18
	v_readlane_b32 s16, v251, 19
	v_readlane_b32 s17, v251, 20
	v_readlane_b32 s18, v251, 21
	v_readlane_b32 s19, v251, 22
	v_readlane_b32 s20, v251, 23
	v_readlane_b32 s21, v251, 24
	v_readlane_b32 s22, v251, 25
	v_readlane_b32 s23, v251, 26
	s_add_u32 s6, s2, s6
	v_lshl_add_u64 v[30:31], v[4:5], 2, s[12:13]
	v_readlane_b32 s8, v249, 26
	s_addc_u32 s7, s3, s7
	v_lshl_add_u64 v[26:27], s[2:3], 0, v[16:17]
	s_lshl_b64 s[2:3], s[72:73], 21
	v_readlane_b32 s12, v249, 30
	v_lshl_add_u64 v[24:25], s[6:7], 0, v[16:17]
	v_readlane_b32 s13, v249, 31
	s_add_u32 s6, s12, s2
	s_addc_u32 s7, s13, s3
	v_ashrrev_i32_e32 v11, 31, v10
	s_add_u32 s2, s28, s2
	v_lshlrev_b64 v[2:3], 13, v[10:11]
	s_addc_u32 s3, s29, s3
	v_lshl_add_u64 v[32:33], s[6:7], 0, v[2:3]
	v_lshl_add_u64 v[2:3], s[2:3], 0, v[2:3]
	v_lshl_add_u64 v[2:3], v[2:3], 0, v[20:21]
	v_lshl_add_u64 v[34:35], s[64:65], 0, v[2:3]
	v_lshl_add_u64 v[2:3], s[56:57], 0, v[10:11]
	v_readlane_b32 s9, v249, 27
	v_lshlrev_b64 v[2:3], 13, v[2:3]
	v_readlane_b32 s62, v249, 44
	v_readlane_b32 s63, v249, 45
	v_readlane_b32 s66, v249, 48
	v_readlane_b32 s67, v249, 49
	v_readlane_b32 s20, v249, 38
	v_lshl_or_b32 v0, v10, 9, v8
	v_lshl_add_u64 v[40:41], s[8:9], 0, v[2:3]
	v_lshl_add_u64 v[2:3], v[2:3], 0, v[20:21]
	s_mov_b32 s50, 0
	v_lshl_add_u64 v[28:29], s[62:63], 0, v[20:21]
	v_add_u32_e32 v36, s70, v10
	v_add_u32_e32 v0, 16, v0
	v_lshl_add_u32 v38, v10, 1, s4
	v_lshl_add_u64 v[42:43], s[62:63], 0, v[2:3]
	s_mov_b64 s[66:67], 0
	s_movk_i32 s20, 0x600
	v_readlane_b32 s10, v249, 28
	v_readlane_b32 s11, v249, 29
	v_readlane_b32 s14, v249, 32
	v_readlane_b32 s15, v249, 33
	v_readlane_b32 s16, v249, 34
	v_readlane_b32 s17, v249, 35
	v_readlane_b32 s18, v249, 36
	v_readlane_b32 s19, v249, 37
	v_readlane_b32 s21, v249, 39
	v_readlane_b32 s22, v249, 40
	v_readlane_b32 s23, v249, 41
	s_cmp_lg_u32 s71, 6
	s_cbranch_scc1 .LBB0_198
	s_mov_b64 s[4:5], 0x20000
	s_and_b64 vcc, exec, s[54:55]
	s_cbranch_vccz .Lg5_ctx
	v_lshl_add_u64 v[52:53], v[40:41], 0, v[20:21]
	v_mov_b32_e32 v54, v42
	v_mov_b32_e32 v55, v43
	s_mov_b64 s[2:3], s[58:59]
	s_branch .Lg5_common
.Lg5_ctx:
	v_readlane_b32 s2, v248, 20
	v_readlane_b32 s3, v248, 21
	v_mov_b32_e32 v56, v10
	v_mov_b32_e32 v57, 0
	v_lshlrev_b64 v[56:57], 11, v[56:57]
	v_readlane_b32 s8, v249, 30
	v_readlane_b32 s9, v249, 31
	v_lshl_add_u64 v[56:57], v[56:57], 0, s[2:3]
	v_lshlrev_b64 v[56:57], 2, v[56:57]
	v_lshl_add_u64 v[54:55], v[22:23], 0, v[56:57]
	v_lshl_add_u64 v[52:53], s[8:9], 0, v[56:57]
	v_lshl_add_u64 v[52:53], v[52:53], 0, v[20:21]
	s_mov_b64 s[2:3], s[60:61]
; DEVI void gemm256(const P& p, const u16* A, int lda, const u16* Bt, int ldb, int K, int brow, int bcol, int mode,
;                         int aux, int layer, int bmode) {
;     ...
;           if (trow == 0) {
;             xb = (float*)(ws + O_XC) + ((size_t)bb * CTXL + R) * D + col;
;             xs = (layer == 0) ? p.ctx + ((size_t)bb * CTXL + R) * D + col : xb;
;             gv = (const float*)(ws + O_MOD) + ((size_t)layer * 5 + 4) * 6144 + 4096 + col;
;           } else {
;             xb = p.out + ((size_t)bb * SEQ + (trow - CTXL) + R) * D + col;
;             xs = (layer == 0) ? p.x + ((size_t)bb * SEQ + (trow - CTXL) + R) * D + col : xb;
;             gv = (const float*)(ws + O_MOD) + ((size_t)layer * 5 + bb) * 6144 + 4096 + col;
;           }
;           f32x4 x0 = *(const f32x4*)xs, x1 = *(const f32x4*)(xs + 4);
;           f32x4 g0 = *(const f32x4*)gv, g1 = *(const f32x4*)(gv + 4);
; #pragma unroll
;           for (int e = 0; e < 4; ++e) { x0[e] += PROBE_US * g0[e] * v[e]; x1[e] += PROBE_US * g1[e] * v[4 + e]; }
;           *(f32x4*)xb = x0;
;           *(f32x4*)(xb + 4) = x1;
.Lg5_common:
	v_lshl_add_u64 v[56:57], s[2:3], 0, v[20:21]
	v_cndmask_b32_e64 v53, v55, v53, s[42:43]
	v_cndmask_b32_e64 v52, v54, v52, s[42:43]
	v_add_u32_e32 v168, 0x10000, v0
	global_load_dwordx4 v[44:47], v[56:57], off
	global_load_dwordx4 v[48:51], v[56:57], off offset:16
	global_load_dwordx4 v[66:69], v[52:53], off
	global_load_dwordx4 v[70:73], v[52:53], off offset:16
	v_lshl_add_u64 v[52:53], v[52:53], 0, s[4:5]
	global_load_dwordx4 v[74:77], v[52:53], off
	global_load_dwordx4 v[78:81], v[52:53], off offset:16
	v_lshl_add_u64 v[52:53], v[52:53], 0, s[4:5]
	global_load_dwordx4 v[82:85], v[52:53], off
	global_load_dwordx4 v[86:89], v[52:53], off offset:16
	v_lshl_add_u64 v[52:53], v[52:53], 0, s[4:5]
	global_load_dwordx4 v[90:93], v[52:53], off
	global_load_dwordx4 v[94:97], v[52:53], off offset:16
	v_lshl_add_u64 v[52:53], v[52:53], 0, s[4:5]
	global_load_dwordx4 v[98:101], v[52:53], off
	global_load_dwordx4 v[102:105], v[52:53], off offset:16
	v_lshl_add_u64 v[52:53], v[52:53], 0, s[4:5]
	global_load_dwordx4 v[106:109], v[52:53], off
	global_load_dwordx4 v[110:113], v[52:53], off offset:16
	v_lshl_add_u64 v[52:53], v[52:53], 0, s[4:5]
	global_load_dwordx4 v[114:117], v[52:53], off
	global_load_dwordx4 v[118:121], v[52:53], off offset:16
	v_lshl_add_u64 v[52:53], v[52:53], 0, s[4:5]
	global_load_dwordx4 v[122:125], v[52:53], off
	global_load_dwordx4 v[126:129], v[52:53], off offset:16
	v_lshl_add_u64 v[52:53], v[52:53], 0, s[4:5]
	global_load_dwordx4 v[204:207], v[52:53], off
	global_load_dwordx4 v[208:211], v[52:53], off offset:16
	v_lshl_add_u64 v[52:53], v[52:53], 0, s[4:5]
	global_load_dwordx4 v[212:215], v[52:53], off
	global_load_dwordx4 v[216:219], v[52:53], off offset:16
	v_lshl_add_u64 v[52:53], v[52:53], 0, s[4:5]
	global_load_dwordx4 v[220:223], v[52:53], off
	global_load_dwordx4 v[224:227], v[52:53], off offset:16
	v_lshl_add_u64 v[52:53], v[52:53], 0, s[4:5]
	global_load_dwordx4 v[228:231], v[52:53], off
	global_load_dwordx4 v[232:235], v[52:53], off offset:16
	v_lshl_add_u64 v[52:53], v[52:53], 0, s[4:5]
	global_load_dwordx4 v[236:239], v[52:53], off
	global_load_dwordx4 v[240:243], v[52:53], off offset:16
	v_lshl_add_u64 v[52:53], v[52:53], 0, s[4:5]
	global_load_dwordx4 v[244:247], v[52:53], off
	global_load_dwordx4 v[172:175], v[52:53], off offset:16
	v_lshl_add_u64 v[52:53], v[52:53], 0, s[4:5]
	global_load_dwordx4 v[176:179], v[52:53], off
	global_load_dwordx4 v[180:183], v[52:53], off offset:16
	v_lshl_add_u64 v[52:53], v[52:53], 0, s[4:5]
	global_load_dwordx4 v[184:187], v[52:53], off
	global_load_dwordx4 v[188:191], v[52:53], off offset:16
	ds_read_b128 v[136:139], v0
	ds_read_b128 v[140:143], v0 offset:8192
	ds_read_b128 v[144:147], v0 offset:16384
	ds_read_b128 v[148:151], v0 offset:24576
	ds_read_b128 v[152:155], v0 offset:32768
	ds_read_b128 v[156:159], v0 offset:40960
	ds_read_b128 v[160:163], v0 offset:49152
	ds_read_b128 v[164:167], v0 offset:57344
	s_waitcnt vmcnt(30) lgkmcnt(7)
	v_lshlrev_b32_e32 v56, 16, v136
	v_and_b32_e32 v57, 0xffff0000, v136
	v_lshlrev_b32_e32 v58, 16, v137
	v_and_b32_e32 v59, 0xffff0000, v137
	v_lshlrev_b32_e32 v60, 16, v138
	v_and_b32_e32 v61, 0xffff0000, v138
	v_lshlrev_b32_e32 v62, 16, v139
	v_and_b32_e32 v63, 0xffff0000, v139
	v_pk_fma_f32 v[66:67], v[44:45], v[56:57], v[66:67]
	v_pk_fma_f32 v[68:69], v[46:47], v[58:59], v[68:69]
	v_pk_fma_f32 v[70:71], v[48:49], v[60:61], v[70:71]
	v_pk_fma_f32 v[72:73], v[50:51], v[62:63], v[72:73]
	global_store_dwordx4 v[54:55], v[66:69], off
	global_store_dwordx4 v[54:55], v[70:73], off offset:16
	v_lshl_add_u64 v[54:55], v[54:55], 0, s[4:5]
	s_waitcnt vmcnt(30) lgkmcnt(6)
	v_lshlrev_b32_e32 v56, 16, v140
	v_and_b32_e32 v57, 0xffff0000, v140
	v_lshlrev_b32_e32 v58, 16, v141
	v_and_b32_e32 v59, 0xffff0000, v141
	v_lshlrev_b32_e32 v60, 16, v142
	v_and_b32_e32 v61, 0xffff0000, v142
	v_lshlrev_b32_e32 v62, 16, v143
	v_and_b32_e32 v63, 0xffff0000, v143
	v_pk_fma_f32 v[74:75], v[44:45], v[56:57], v[74:75]
	v_pk_fma_f32 v[76:77], v[46:47], v[58:59], v[76:77]
	v_pk_fma_f32 v[78:79], v[48:49], v[60:61], v[78:79]
	v_pk_fma_f32 v[80:81], v[50:51], v[62:63], v[80:81]
	global_store_dwordx4 v[54:55], v[74:77], off
	global_store_dwordx4 v[54:55], v[78:81], off offset:16
	v_lshl_add_u64 v[54:55], v[54:55], 0, s[4:5]
	s_waitcnt vmcnt(30) lgkmcnt(5)
	v_lshlrev_b32_e32 v56, 16, v144
	v_and_b32_e32 v57, 0xffff0000, v144
	v_lshlrev_b32_e32 v58, 16, v145
	v_and_b32_e32 v59, 0xffff0000, v145
	v_lshlrev_b32_e32 v60, 16, v146
	v_and_b32_e32 v61, 0xffff0000, v146
	v_lshlrev_b32_e32 v62, 16, v147
	v_and_b32_e32 v63, 0xffff0000, v147
	v_pk_fma_f32 v[82:83], v[44:45], v[56:57], v[82:83]
	v_pk_fma_f32 v[84:85], v[46:47], v[58:59], v[84:85]
	v_pk_fma_f32 v[86:87], v[48:49], v[60:61], v[86:87]
	v_pk_fma_f32 v[88:89], v[50:51], v[62:63], v[88:89]
	global_store_dwordx4 v[54:55], v[82:85], off
	global_store_dwordx4 v[54:55], v[86:89], off offset:16
	v_lshl_add_u64 v[54:55], v[54:55], 0, s[4:5]
	s_waitcnt vmcnt(30) lgkmcnt(4)
	v_lshlrev_b32_e32 v56, 16, v148
	v_and_b32_e32 v57, 0xffff0000, v148
	v_lshlrev_b32_e32 v58, 16, v149
	v_and_b32_e32 v59, 0xffff0000, v149
	v_lshlrev_b32_e32 v60, 16, v150
	v_and_b32_e32 v61, 0xffff0000, v150
	v_lshlrev_b32_e32 v62, 16, v151
	v_and_b32_e32 v63, 0xffff0000, v151
	v_pk_fma_f32 v[90:91], v[44:45], v[56:57], v[90:91]
	v_pk_fma_f32 v[92:93], v[46:47], v[58:59], v[92:93]
	v_pk_fma_f32 v[94:95], v[48:49], v[60:61], v[94:95]
	v_pk_fma_f32 v[96:97], v[50:51], v[62:63], v[96:97]
	global_store_dwordx4 v[54:55], v[90:93], off
	global_store_dwordx4 v[54:55], v[94:97], off offset:16
	v_lshl_add_u64 v[54:55], v[54:55], 0, s[4:5]
	s_waitcnt vmcnt(30) lgkmcnt(3)
; DEVI void gemm256(const P& p, const u16* A, int lda, const u16* Bt, int ldb, int K, int brow, int bcol, int mode,
;                         int aux, int layer, int bmode) {
;     ...
;           f32x4 x0 = *(const f32x4*)xs, x1 = *(const f32x4*)(xs + 4);
;           f32x4 g0 = *(const f32x4*)gv, g1 = *(const f32x4*)(gv + 4);
; #pragma unroll
;           for (int e = 0; e < 4; ++e) { x0[e] += PROBE_US * g0[e] * v[e]; x1[e] += PROBE_US * g1[e] * v[4 + e]; }
;           *(f32x4*)xb = x0;
;           *(f32x4*)(xb + 4) = x1;
	v_lshlrev_b32_e32 v56, 16, v152
	v_and_b32_e32 v57, 0xffff0000, v152
	v_lshlrev_b32_e32 v58, 16, v153
	v_and_b32_e32 v59, 0xffff0000, v153
	v_lshlrev_b32_e32 v60, 16, v154
	v_and_b32_e32 v61, 0xffff0000, v154
	v_lshlrev_b32_e32 v62, 16, v155
	v_and_b32_e32 v63, 0xffff0000, v155
	v_pk_fma_f32 v[98:99], v[44:45], v[56:57], v[98:99]
	v_pk_fma_f32 v[100:101], v[46:47], v[58:59], v[100:101]
	v_pk_fma_f32 v[102:103], v[48:49], v[60:61], v[102:103]
	v_pk_fma_f32 v[104:105], v[50:51], v[62:63], v[104:105]
	global_store_dwordx4 v[54:55], v[98:101], off
	global_store_dwordx4 v[54:55], v[102:105], off offset:16
	v_lshl_add_u64 v[54:55], v[54:55], 0, s[4:5]
	s_waitcnt vmcnt(30) lgkmcnt(2)
	v_lshlrev_b32_e32 v56, 16, v156
	v_and_b32_e32 v57, 0xffff0000, v156
	v_lshlrev_b32_e32 v58, 16, v157
	v_and_b32_e32 v59, 0xffff0000, v157
	v_lshlrev_b32_e32 v60, 16, v158
	v_and_b32_e32 v61, 0xffff0000, v158
	v_lshlrev_b32_e32 v62, 16, v159
	v_and_b32_e32 v63, 0xffff0000, v159
	v_pk_fma_f32 v[106:107], v[44:45], v[56:57], v[106:107]
	v_pk_fma_f32 v[108:109], v[46:47], v[58:59], v[108:109]
	v_pk_fma_f32 v[110:111], v[48:49], v[60:61], v[110:111]
	v_pk_fma_f32 v[112:113], v[50:51], v[62:63], v[112:113]
	global_store_dwordx4 v[54:55], v[106:109], off
	global_store_dwordx4 v[54:55], v[110:113], off offset:16
	v_lshl_add_u64 v[54:55], v[54:55], 0, s[4:5]
	s_waitcnt vmcnt(30) lgkmcnt(1)
	v_lshlrev_b32_e32 v56, 16, v160
	v_and_b32_e32 v57, 0xffff0000, v160
	v_lshlrev_b32_e32 v58, 16, v161
	v_and_b32_e32 v59, 0xffff0000, v161
	v_lshlrev_b32_e32 v60, 16, v162
	v_and_b32_e32 v61, 0xffff0000, v162
	v_lshlrev_b32_e32 v62, 16, v163
	v_and_b32_e32 v63, 0xffff0000, v163
	v_pk_fma_f32 v[114:115], v[44:45], v[56:57], v[114:115]
	v_pk_fma_f32 v[116:117], v[46:47], v[58:59], v[116:117]
	v_pk_fma_f32 v[118:119], v[48:49], v[60:61], v[118:119]
	v_pk_fma_f32 v[120:121], v[50:51], v[62:63], v[120:121]
	global_store_dwordx4 v[54:55], v[114:117], off
	global_store_dwordx4 v[54:55], v[118:121], off offset:16
	v_lshl_add_u64 v[54:55], v[54:55], 0, s[4:5]
	s_waitcnt vmcnt(30) lgkmcnt(0)
	v_lshlrev_b32_e32 v56, 16, v164
	v_and_b32_e32 v57, 0xffff0000, v164
	v_lshlrev_b32_e32 v58, 16, v165
	v_and_b32_e32 v59, 0xffff0000, v165
	v_lshlrev_b32_e32 v60, 16, v166
	v_and_b32_e32 v61, 0xffff0000, v166
	v_lshlrev_b32_e32 v62, 16, v167
	v_and_b32_e32 v63, 0xffff0000, v167
	v_pk_fma_f32 v[122:123], v[44:45], v[56:57], v[122:123]
	v_pk_fma_f32 v[124:125], v[46:47], v[58:59], v[124:125]
	v_pk_fma_f32 v[126:127], v[48:49], v[60:61], v[126:127]
	v_pk_fma_f32 v[128:129], v[50:51], v[62:63], v[128:129]
	global_store_dwordx4 v[54:55], v[122:125], off
	global_store_dwordx4 v[54:55], v[126:129], off offset:16
	v_lshl_add_u64 v[54:55], v[54:55], 0, s[4:5]
	ds_read_b128 v[136:139], v168
	ds_read_b128 v[140:143], v168 offset:8192
	ds_read_b128 v[144:147], v168 offset:16384
	ds_read_b128 v[148:151], v168 offset:24576
	ds_read_b128 v[152:155], v168 offset:32768
	ds_read_b128 v[156:159], v168 offset:40960
	ds_read_b128 v[160:163], v168 offset:49152
	ds_read_b128 v[164:167], v168 offset:57344
	s_waitcnt vmcnt(30) lgkmcnt(7)
	v_lshlrev_b32_e32 v56, 16, v136
	v_and_b32_e32 v57, 0xffff0000, v136
	v_lshlrev_b32_e32 v58, 16, v137
	v_and_b32_e32 v59, 0xffff0000, v137
	v_lshlrev_b32_e32 v60, 16, v138
	v_and_b32_e32 v61, 0xffff0000, v138
	v_lshlrev_b32_e32 v62, 16, v139
	v_and_b32_e32 v63, 0xffff0000, v139
	v_pk_fma_f32 v[204:205], v[44:45], v[56:57], v[204:205]
	v_pk_fma_f32 v[206:207], v[46:47], v[58:59], v[206:207]
	v_pk_fma_f32 v[208:209], v[48:49], v[60:61], v[208:209]
	v_pk_fma_f32 v[210:211], v[50:51], v[62:63], v[210:211]
	global_store_dwordx4 v[54:55], v[204:207], off
	global_store_dwordx4 v[54:55], v[208:211], off offset:16
	v_lshl_add_u64 v[54:55], v[54:55], 0, s[4:5]
	s_waitcnt vmcnt(30) lgkmcnt(6)
	v_lshlrev_b32_e32 v56, 16, v140
	v_and_b32_e32 v57, 0xffff0000, v140
	v_lshlrev_b32_e32 v58, 16, v141
	v_and_b32_e32 v59, 0xffff0000, v141
	v_lshlrev_b32_e32 v60, 16, v142
	v_and_b32_e32 v61, 0xffff0000, v142
	v_lshlrev_b32_e32 v62, 16, v143
	v_and_b32_e32 v63, 0xffff0000, v143
	v_pk_fma_f32 v[212:213], v[44:45], v[56:57], v[212:213]
	v_pk_fma_f32 v[214:215], v[46:47], v[58:59], v[214:215]
	v_pk_fma_f32 v[216:217], v[48:49], v[60:61], v[216:217]
	v_pk_fma_f32 v[218:219], v[50:51], v[62:63], v[218:219]
	global_store_dwordx4 v[54:55], v[212:215], off
	global_store_dwordx4 v[54:55], v[216:219], off offset:16
	v_lshl_add_u64 v[54:55], v[54:55], 0, s[4:5]
	s_waitcnt vmcnt(30) lgkmcnt(5)
; DEVI void gemm256(const P& p, const u16* A, int lda, const u16* Bt, int ldb, int K, int brow, int bcol, int mode,
;                         int aux, int layer, int bmode) {
;     ...
;           f32x4 x0 = *(const f32x4*)xs, x1 = *(const f32x4*)(xs + 4);
;           f32x4 g0 = *(const f32x4*)gv, g1 = *(const f32x4*)(gv + 4);
; #pragma unroll
;           for (int e = 0; e < 4; ++e) { x0[e] += PROBE_US * g0[e] * v[e]; x1[e] += PROBE_US * g1[e] * v[4 + e]; }
;           *(f32x4*)xb = x0;
;           *(f32x4*)(xb + 4) = x1;
	v_lshlrev_b32_e32 v56, 16, v144
	v_and_b32_e32 v57, 0xffff0000, v144
	v_lshlrev_b32_e32 v58, 16, v145
	v_and_b32_e32 v59, 0xffff0000, v145
	v_lshlrev_b32_e32 v60, 16, v146
	v_and_b32_e32 v61, 0xffff0000, v146
	v_lshlrev_b32_e32 v62, 16, v147
	v_and_b32_e32 v63, 0xffff0000, v147
	v_pk_fma_f32 v[220:221], v[44:45], v[56:57], v[220:221]
	v_pk_fma_f32 v[222:223], v[46:47], v[58:59], v[222:223]
	v_pk_fma_f32 v[224:225], v[48:49], v[60:61], v[224:225]
	v_pk_fma_f32 v[226:227], v[50:51], v[62:63], v[226:227]
	global_store_dwordx4 v[54:55], v[220:223], off
	global_store_dwordx4 v[54:55], v[224:227], off offset:16
	v_lshl_add_u64 v[54:55], v[54:55], 0, s[4:5]
	s_waitcnt vmcnt(30) lgkmcnt(4)
	v_lshlrev_b32_e32 v56, 16, v148
	v_and_b32_e32 v57, 0xffff0000, v148
	v_lshlrev_b32_e32 v58, 16, v149
	v_and_b32_e32 v59, 0xffff0000, v149
	v_lshlrev_b32_e32 v60, 16, v150
	v_and_b32_e32 v61, 0xffff0000, v150
	v_lshlrev_b32_e32 v62, 16, v151
	v_and_b32_e32 v63, 0xffff0000, v151
	v_pk_fma_f32 v[228:229], v[44:45], v[56:57], v[228:229]
	v_pk_fma_f32 v[230:231], v[46:47], v[58:59], v[230:231]
	v_pk_fma_f32 v[232:233], v[48:49], v[60:61], v[232:233]
	v_pk_fma_f32 v[234:235], v[50:51], v[62:63], v[234:235]
	global_store_dwordx4 v[54:55], v[228:231], off
	global_store_dwordx4 v[54:55], v[232:235], off offset:16
	v_lshl_add_u64 v[54:55], v[54:55], 0, s[4:5]
	s_waitcnt vmcnt(30) lgkmcnt(3)
	v_lshlrev_b32_e32 v56, 16, v152
	v_and_b32_e32 v57, 0xffff0000, v152
	v_lshlrev_b32_e32 v58, 16, v153
	v_and_b32_e32 v59, 0xffff0000, v153
	v_lshlrev_b32_e32 v60, 16, v154
	v_and_b32_e32 v61, 0xffff0000, v154
	v_lshlrev_b32_e32 v62, 16, v155
	v_and_b32_e32 v63, 0xffff0000, v155
	v_pk_fma_f32 v[236:237], v[44:45], v[56:57], v[236:237]
	v_pk_fma_f32 v[238:239], v[46:47], v[58:59], v[238:239]
	v_pk_fma_f32 v[240:241], v[48:49], v[60:61], v[240:241]
	v_pk_fma_f32 v[242:243], v[50:51], v[62:63], v[242:243]
	global_store_dwordx4 v[54:55], v[236:239], off
	global_store_dwordx4 v[54:55], v[240:243], off offset:16
	v_lshl_add_u64 v[54:55], v[54:55], 0, s[4:5]
	s_waitcnt vmcnt(30) lgkmcnt(2)
	v_lshlrev_b32_e32 v56, 16, v156
	v_and_b32_e32 v57, 0xffff0000, v156
	v_lshlrev_b32_e32 v58, 16, v157
	v_and_b32_e32 v59, 0xffff0000, v157
	v_lshlrev_b32_e32 v60, 16, v158
	v_and_b32_e32 v61, 0xffff0000, v158
	v_lshlrev_b32_e32 v62, 16, v159
	v_and_b32_e32 v63, 0xffff0000, v159
	v_pk_fma_f32 v[244:245], v[44:45], v[56:57], v[244:245]
	v_pk_fma_f32 v[246:247], v[46:47], v[58:59], v[246:247]
	v_pk_fma_f32 v[172:173], v[48:49], v[60:61], v[172:173]
	v_pk_fma_f32 v[174:175], v[50:51], v[62:63], v[174:175]
	global_store_dwordx4 v[54:55], v[244:247], off
	global_store_dwordx4 v[54:55], v[172:175], off offset:16
	v_lshl_add_u64 v[54:55], v[54:55], 0, s[4:5]
	s_waitcnt vmcnt(30) lgkmcnt(1)
	v_lshlrev_b32_e32 v56, 16, v160
	v_and_b32_e32 v57, 0xffff0000, v160
	v_lshlrev_b32_e32 v58, 16, v161
	v_and_b32_e32 v59, 0xffff0000, v161
	v_lshlrev_b32_e32 v60, 16, v162
	v_and_b32_e32 v61, 0xffff0000, v162
	v_lshlrev_b32_e32 v62, 16, v163
	v_and_b32_e32 v63, 0xffff0000, v163
	v_pk_fma_f32 v[176:177], v[44:45], v[56:57], v[176:177]
	v_pk_fma_f32 v[178:179], v[46:47], v[58:59], v[178:179]
	v_pk_fma_f32 v[180:181], v[48:49], v[60:61], v[180:181]
	v_pk_fma_f32 v[182:183], v[50:51], v[62:63], v[182:183]
	global_store_dwordx4 v[54:55], v[176:179], off
	global_store_dwordx4 v[54:55], v[180:183], off offset:16
	v_lshl_add_u64 v[54:55], v[54:55], 0, s[4:5]
	s_waitcnt vmcnt(30) lgkmcnt(0)
	v_lshlrev_b32_e32 v56, 16, v164
	v_and_b32_e32 v57, 0xffff0000, v164
	v_lshlrev_b32_e32 v58, 16, v165
	v_and_b32_e32 v59, 0xffff0000, v165
	v_lshlrev_b32_e32 v60, 16, v166
	v_and_b32_e32 v61, 0xffff0000, v166
	v_lshlrev_b32_e32 v62, 16, v167
	v_and_b32_e32 v63, 0xffff0000, v167
	v_pk_fma_f32 v[184:185], v[44:45], v[56:57], v[184:185]
	v_pk_fma_f32 v[186:187], v[46:47], v[58:59], v[186:187]
	v_pk_fma_f32 v[188:189], v[48:49], v[60:61], v[188:189]
	v_pk_fma_f32 v[190:191], v[50:51], v[62:63], v[190:191]
	global_store_dwordx4 v[54:55], v[184:187], off
	global_store_dwordx4 v[54:55], v[188:191], off offset:16
	s_branch .LBB0_305
